# v5 + prep W_in transpose: the four row-block loads of a tile issued together instead of one exposed round trip each
# speedup vs baseline: 1.0063x; 1.0060x over previous
; DEVI void transpose_tile(const float* __restrict__ src, bfu* __restrict__ dst, int R, int C, int r0, int c0, float* tile, int tid) {
;   __syncthreads();
;   {
;     int tx = tid & 15, ty = tid >> 4;
; #pragma unroll
;     for (int i = 0; i < 4; ++i) {
;       int r = ty + i * 16;
;       float4 v = *reinterpret_cast<const float4*>(src + (long)(r0 + r) * C + c0 + tx * 4);
;       float* tp = tile + r * 65 + tx * 4;
;       tp[0] = v.x; tp[1] = v.y; tp[2] = v.z; tp[3] = v.w;
;     }
;   }
;   __syncthreads();
;   {
;     int c = tid >> 2, rs = (tid & 3) * 16;
;     unsigned pk[8];
; #pragma unroll
;     for (int i = 0; i < 8; ++i) {
;       unsigned lo = f2b(tile[(rs + 2 * i) * 65 + c]);
;       unsigned hi = f2b(tile[(rs + 2 * i + 1) * 65 + c]);
;       pk[i] = lo | (hi << 16);
;     }
;     uint4* dp = reinterpret_cast<uint4*>(dst + (long)(c0 + c) * R + r0 + rs);
;     dp[0] = make_uint4(pk[0], pk[1], pk[2], pk[3]);
;     dp[1] = make_uint4(pk[4], pk[5], pk[6], pk[7]);
;   }
; }
; DEVI void phase_prep(const Params& P, int l, char* smem) {
;     ...
;     if (id < T0) {
;       int tr = id / 192, tc = id % 192;
;       transpose_tile(P.in[6] + (long)l * 1024 * 12288, (bfu*)(ws + O_WIN), 1024, 12288, tr * 64, tc * 64, tile, tid);
.LBB0_35:
	s_andn2_b64 vcc, exec, s[44:45]
	s_cbranch_vccnz .LBB0_8
	s_mul_hi_i32 s24, s51, 0x2aaaaaab
	s_lshr_b32 s44, s24, 31
	s_ashr_i32 s24, s24, 5
	s_add_i32 s24, s24, s44
	s_lshl_b32 s44, s24, 6
	s_mulk_i32 s24, 0xd000
	s_add_i32 s52, s50, s24
	s_ashr_i32 s53, s52, 31
	v_lshl_add_u64 v[30:31], s[52:53], 2, v[22:23]
	v_add_u32_e32 v25, s44, v33
	s_mov_b32 s4, 0xc000
	v_mad_i64_i32 v[26:27], s[54:55], v25, s4, v[30:31]
	s_barrier
	global_load_dwordx4 v[208:211], v[26:27], off
	v_add_u32_e32 v25, s44, v34
	s_ashr_i32 s45, s44, 31
	v_mad_i64_i32 v[26:27], s[54:55], v25, s4, v[30:31]
	global_load_dwordx4 v[212:215], v[26:27], off
	v_add_u32_e32 v25, s44, v35
	v_mad_i64_i32 v[26:27], s[54:55], v25, s4, v[30:31]
	global_load_dwordx4 v[216:219], v[26:27], off
	v_add_u32_e32 v25, s44, v36
	v_mad_i64_i32 v[26:27], s[54:55], v25, s4, v[30:31]
	global_load_dwordx4 v[26:29], v[26:27], off
	s_waitcnt vmcnt(3)
	ds_write2_b32 v39, v208, v209 offset1:1
	ds_write2_b32 v39, v210, v211 offset0:2 offset1:3
	s_waitcnt vmcnt(2)
	ds_write2_b32 v40, v212, v213 offset1:1
	ds_write2_b32 v41, v214, v215 offset1:1
	s_waitcnt vmcnt(1)
	ds_write2_b32 v42, v216, v217 offset1:1
	ds_write2_b32 v43, v218, v219 offset1:1
	v_add_u32_e32 v30, s52, v37
	v_ashrrev_i32_e32 v31, 31, v30
	v_lshlrev_b64 v[30:31], 11, v[30:31]
	v_lshl_add_u64 v[30:31], v[0:1], 0, v[30:31]
	v_lshl_add_u64 v[30:31], s[44:45], 1, v[30:31]
	v_lshl_add_u64 v[30:31], v[30:31], 0, v[88:89]
	s_waitcnt vmcnt(0)
	ds_write2_b32 v44, v26, v27 offset1:1
	ds_write2_b32 v45, v28, v29 offset1:1
	s_waitcnt lgkmcnt(0)
	s_barrier
	ds_read2_b32 v[50:51], v38 offset1:65
	ds_read2_b32 v[52:53], v38 offset0:130 offset1:195
	ds_read2_b32 v[54:55], v46 offset0:4 offset1:69
	ds_read2_b32 v[56:57], v46 offset0:134 offset1:199
	ds_read2_b32 v[58:59], v47 offset0:8 offset1:73
	ds_read2_b32 v[60:61], v47 offset0:138 offset1:203
	ds_read2_b32 v[26:27], v48 offset0:12 offset1:77
	ds_read2_b32 v[28:29], v48 offset0:142 offset1:207
	s_waitcnt lgkmcnt(6)
	v_and_b32_sdwa v25, v52, v95 dst_sel:DWORD dst_unused:UNUSED_PAD src0_sel:WORD_1 src1_sel:DWORD
	v_and_b32_sdwa v49, v50, v95 dst_sel:DWORD dst_unused:UNUSED_PAD src0_sel:WORD_1 src1_sel:DWORD
	v_add3_u32 v49, v50, v49, s39
	v_add3_u32 v25, v52, v25, s39
	v_and_b32_sdwa v50, v53, v95 dst_sel:DWORD dst_unused:UNUSED_PAD src0_sel:WORD_1 src1_sel:DWORD
	v_and_b32_sdwa v52, v51, v95 dst_sel:DWORD dst_unused:UNUSED_PAD src0_sel:WORD_1 src1_sel:DWORD
	v_add3_u32 v50, v53, v50, s39
	v_add3_u32 v51, v51, v52, s39
	v_and_b32_e32 v50, 0xffff0000, v50
	v_and_b32_e32 v52, 0xffff0000, v51
	v_or_b32_sdwa v51, v50, v25 dst_sel:DWORD dst_unused:UNUSED_PAD src0_sel:DWORD src1_sel:WORD_1
	v_or_b32_sdwa v50, v52, v49 dst_sel:DWORD dst_unused:UNUSED_PAD src0_sel:DWORD src1_sel:WORD_1
	s_waitcnt lgkmcnt(4)
	v_and_b32_sdwa v52, v57, v95 dst_sel:DWORD dst_unused:UNUSED_PAD src0_sel:WORD_1 src1_sel:DWORD
	v_and_b32_sdwa v53, v55, v95 dst_sel:DWORD dst_unused:UNUSED_PAD src0_sel:WORD_1 src1_sel:DWORD
	v_and_b32_sdwa v25, v56, v95 dst_sel:DWORD dst_unused:UNUSED_PAD src0_sel:WORD_1 src1_sel:DWORD
	v_and_b32_sdwa v49, v54, v95 dst_sel:DWORD dst_unused:UNUSED_PAD src0_sel:WORD_1 src1_sel:DWORD
	v_add3_u32 v52, v57, v52, s39
	v_add3_u32 v53, v55, v53, s39
	v_add3_u32 v49, v54, v49, s39
	v_add3_u32 v25, v56, v25, s39
	v_and_b32_e32 v52, 0xffff0000, v52
	v_and_b32_e32 v54, 0xffff0000, v53
	v_or_b32_sdwa v53, v52, v25 dst_sel:DWORD dst_unused:UNUSED_PAD src0_sel:DWORD src1_sel:WORD_1
	v_or_b32_sdwa v52, v54, v49 dst_sel:DWORD dst_unused:UNUSED_PAD src0_sel:DWORD src1_sel:WORD_1
	global_store_dwordx4 v[30:31], v[50:53], off
	s_waitcnt lgkmcnt(2)
	v_and_b32_sdwa v25, v60, v95 dst_sel:DWORD dst_unused:UNUSED_PAD src0_sel:WORD_1 src1_sel:DWORD
	v_and_b32_sdwa v49, v58, v95 dst_sel:DWORD dst_unused:UNUSED_PAD src0_sel:WORD_1 src1_sel:DWORD
	v_and_b32_sdwa v50, v61, v95 dst_sel:DWORD dst_unused:UNUSED_PAD src0_sel:WORD_1 src1_sel:DWORD
	v_and_b32_sdwa v51, v59, v95 dst_sel:DWORD dst_unused:UNUSED_PAD src0_sel:WORD_1 src1_sel:DWORD
	v_add3_u32 v50, v61, v50, s39
	v_add3_u32 v51, v59, v51, s39
	v_add3_u32 v49, v58, v49, s39
	v_add3_u32 v25, v60, v25, s39
	v_and_b32_e32 v50, 0xffff0000, v50
	v_and_b32_e32 v52, 0xffff0000, v51
	v_or_b32_sdwa v51, v50, v25 dst_sel:DWORD dst_unused:UNUSED_PAD src0_sel:DWORD src1_sel:WORD_1
	v_or_b32_sdwa v50, v52, v49 dst_sel:DWORD dst_unused:UNUSED_PAD src0_sel:DWORD src1_sel:WORD_1
	s_waitcnt lgkmcnt(0)
	v_and_b32_sdwa v25, v28, v95 dst_sel:DWORD dst_unused:UNUSED_PAD src0_sel:WORD_1 src1_sel:DWORD
	v_and_b32_sdwa v49, v26, v95 dst_sel:DWORD dst_unused:UNUSED_PAD src0_sel:WORD_1 src1_sel:DWORD
	v_add3_u32 v26, v26, v49, s39
	v_add3_u32 v25, v28, v25, s39
	v_and_b32_sdwa v28, v29, v95 dst_sel:DWORD dst_unused:UNUSED_PAD src0_sel:WORD_1 src1_sel:DWORD
	v_and_b32_sdwa v49, v27, v95 dst_sel:DWORD dst_unused:UNUSED_PAD src0_sel:WORD_1 src1_sel:DWORD
	v_add3_u32 v28, v29, v28, s39
	v_add3_u32 v27, v27, v49, s39
	v_and_b32_e32 v28, 0xffff0000, v28
	v_and_b32_e32 v27, 0xffff0000, v27
	v_or_b32_sdwa v53, v28, v25 dst_sel:DWORD dst_unused:UNUSED_PAD src0_sel:DWORD src1_sel:WORD_1
	v_or_b32_sdwa v52, v27, v26 dst_sel:DWORD dst_unused:UNUSED_PAD src0_sel:DWORD src1_sel:WORD_1
	global_store_dwordx4 v[30:31], v[50:53], off offset:16
	s_branch .LBB0_8
